# phase B: one-time s_sleep stagger of waves 4-7 at block-loop entry
# speedup vs baseline: 1.0020x; 1.0020x over previous
.LBB0_1157:
	s_cmp_gt_u32 s79, 63
	s_cselect_b32 s50, s78, 8
	s_cmp_ge_i32 s50, s25
	s_waitcnt lgkmcnt(0)
	s_barrier
	s_cbranch_scc1 .LBB0_1211
	s_add_i32 s6, 0, 0x20000
	v_lshl_add_u32 v227, v74, 5, s6
	v_cmp_lt_u32_e64 s[30:31], 3, v75
	v_cmp_eq_u32_e64 s[34:35], 1, v217
	v_cmp_eq_u32_e64 s[36:37], 2, v217
	s_lshl_b32 s6, s68, 21
	v_lshl_add_u32 v182, v197, 4, s6
	v_add_u32_e32 v182, 0x1000, v182
	v_mov_b32_e32 v183, 0
	v_lshl_add_u64 v[182:183], s[66:67], 0, v[182:183]
	s_mov_b64 s[6:7], 0x3e78400
	v_lshl_add_u64 v[182:183], v[182:183], 0, s[6:7]
	s_mov_b64 s[6:7], 0x600000
	v_lshl_add_u64 v[184:185], v[182:183], 0, s[6:7]
	s_cmp_lt_u32 s78, 4
	s_cbranch_scc1 .Lpb_nostagger
	s_sleep 40
.Lpb_nostagger:
	s_branch .LBB0_1160
.LBB0_1159:
	s_add_i32 s50, s50, 16
	s_cmp_ge_i32 s50, s25
	s_cbranch_scc1 .LBB0_1211
